# code placement: 64-byte alignment of the seven hot loop heads (GEMM K-loops, attention tile loops)
# speedup vs baseline: 1.0056x; 1.0005x over previous
; #define PG8_STAGE(bufoff, gbase, voff) glds16s2((voff)[0], (voff)[1], (const void*)(gbase), ldsn + (unsigned)(bufoff))
; #define PG8_LDA(dst, b, h) do { _Pragma("unroll") for (int m = 0; m < 4; ++m) _Pragma("unroll") for (int k = 0; k < 2; ++k) dst[m][k] = *(const LAS bf16x8*)(lds + PG8_SA(b, h) + aoff + m * 2048 + k * 1024); } while (0)
; #define PG8_LDB(dst, b, h) do { _Pragma("unroll") for (int n = 0; n < 2; ++n) _Pragma("unroll") for (int k = 0; k < 2; ++k) dst[n][k] = *(const LAS bf16x8*)(lds + PG8_SB(b, h) + boff + n * 2048 + k * 1024); } while (0)
; #define PG8_MMA(ai, bj, At, Bt) do { __builtin_amdgcn_s_setprio(1); _Pragma("unroll") for (int m = 0; m < 4; ++m) _Pragma("unroll") for (int n = 0; n < 2; ++n) _Pragma("unroll") for (int k = 0; k < 2; ++k) \
;         acc[ai][bj][m][n] = __builtin_amdgcn_mfma_f32_16x16x32_bf16(Bt[n][k], At[m][k], acc[ai][bj][m][n], 0, 0, 0); __builtin_amdgcn_s_setprio(0); } while (0)
; #define PG8_WAIT_V(n) asm volatile("s_waitcnt vmcnt(" #n ")" ::: "memory")
; #define PG8_WAIT_L(n) asm volatile("s_waitcnt lgkmcnt(" #n ")" ::: "memory")
; #define PG8_BAR __builtin_amdgcn_s_barrier()
; #define PG8_SCHED __builtin_amdgcn_sched_barrier(0)
; template <class Epi, bool ALIGN_EPI, bool EARLY_DRAIN = true, class Pre = NoPre>
; __device__ __forceinline__ void gemm_phase(LAS unsigned char* lds, const Gemm g, const StaticOrder& S, const Epi& E, int wv, const Pre& pre = Pre()) {
;     ...
;             PG8_WAIT_L(0); PG8_BAR; PG8_MMA(0, 0, At, B0); PG8_MMA(0, 1, At, B1); PG8_BAR; PG8_SCHED;
;             PG8_LDA(At, 0, 1); PG8_STAGE(PG8_SB(0, 0), b2, voffB); PG8_STAGE(PG8_SB(0, 1), b2 + bhs, voffB); PG8_STAGE(PG8_SA(0, 0), a2, voffA);
;             if (!lf_) PG8_WAIT_V(8);
;             PG8_WAIT_L(0); PG8_BAR; PG8_MMA(1, 0, At, B0); PG8_MMA(1, 1, At, B1); PG8_BAR; PG8_SCHED;
;             PG8_LDB(B0, 1, 0); PG8_LDB(B1, 1, 1); PG8_SCHED; PG8_LDA(At, 1, 0); PG8_STAGE(PG8_SA(0, 1), a2 + ahs, voffA);
;             if (!lf_) PG8_WAIT_V(8);
;             PG8_WAIT_L(0); PG8_BAR; PG8_MMA(0, 0, At, B0); PG8_MMA(0, 1, At, B1); PG8_BAR; PG8_SCHED;
;             PG8_LDA(At, 1, 1); PG8_STAGE(PG8_SB(1, 0), b3, voffB); PG8_STAGE(PG8_SB(1, 1), b3 + bhs, voffB); PG8_STAGE(PG8_SA(1, 0), a3, voffA);
;             PG8_WAIT_V(8); PG8_WAIT_L(0); PG8_BAR; PG8_MMA(1, 0, At, B0); PG8_MMA(1, 1, At, B1); PG8_BAR; PG8_SCHED;
;         }
.LBB0_177:
	s_add_u32 s36, s84, 0x80
	s_waitcnt lgkmcnt(0)
	s_addc_u32 s37, s85, 0
	s_add_u32 s66, s70, 0x80
	s_addc_u32 s67, s71, 0
	s_barrier
	s_setprio 1
	s_waitcnt lgkmcnt(7)
	v_mfma_f32_16x16x32_bf16 v[122:125], v[146:149], v[186:189], v[122:125]
	v_mfma_f32_16x16x32_bf16 v[114:117], v[154:157], v[186:189], v[114:117]
	s_waitcnt lgkmcnt(5)
	v_mfma_f32_16x16x32_bf16 v[106:109], v[146:149], v[178:181], v[106:109]
	v_mfma_f32_16x16x32_bf16 v[98:101], v[154:157], v[178:181], v[98:101]
	s_waitcnt lgkmcnt(3)
	v_mfma_f32_16x16x32_bf16 v[90:93], v[146:149], v[170:173], v[90:93]
	v_mfma_f32_16x16x32_bf16 v[82:85], v[154:157], v[170:173], v[82:85]
	s_waitcnt lgkmcnt(1)
	v_mfma_f32_16x16x32_bf16 v[62:65], v[146:149], v[162:165], v[62:65]
	v_mfma_f32_16x16x32_bf16 v[50:53], v[154:157], v[162:165], v[50:53]
	v_mfma_f32_16x16x32_bf16 v[122:125], v[150:153], v[190:193], v[122:125]
	v_mfma_f32_16x16x32_bf16 v[114:117], v[158:161], v[190:193], v[114:117]
	v_mfma_f32_16x16x32_bf16 v[106:109], v[150:153], v[182:185], v[106:109]
	v_mfma_f32_16x16x32_bf16 v[98:101], v[158:161], v[182:185], v[98:101]
	v_mfma_f32_16x16x32_bf16 v[90:93], v[150:153], v[174:177], v[90:93]
	v_mfma_f32_16x16x32_bf16 v[82:85], v[158:161], v[174:177], v[82:85]
	s_waitcnt lgkmcnt(0)
	v_mfma_f32_16x16x32_bf16 v[62:65], v[150:153], v[166:169], v[62:65]
	v_mfma_f32_16x16x32_bf16 v[50:53], v[158:161], v[166:169], v[50:53]
	s_setprio 0
	s_setprio 1
	v_mfma_f32_16x16x32_bf16 v[126:129], v[130:133], v[186:189], v[126:129]
	v_mfma_f32_16x16x32_bf16 v[118:121], v[138:141], v[186:189], v[118:121]
	v_mfma_f32_16x16x32_bf16 v[110:113], v[130:133], v[178:181], v[110:113]
	v_mfma_f32_16x16x32_bf16 v[102:105], v[138:141], v[178:181], v[102:105]
	v_mfma_f32_16x16x32_bf16 v[94:97], v[130:133], v[170:173], v[94:97]
	v_mfma_f32_16x16x32_bf16 v[86:89], v[138:141], v[170:173], v[86:89]
	v_mfma_f32_16x16x32_bf16 v[70:73], v[130:133], v[162:165], v[70:73]
	v_mfma_f32_16x16x32_bf16 v[54:57], v[138:141], v[162:165], v[54:57]
	v_mfma_f32_16x16x32_bf16 v[126:129], v[134:137], v[190:193], v[126:129]
	v_mfma_f32_16x16x32_bf16 v[118:121], v[142:145], v[190:193], v[118:121]
	v_mfma_f32_16x16x32_bf16 v[110:113], v[134:137], v[182:185], v[110:113]
	v_mfma_f32_16x16x32_bf16 v[102:105], v[142:145], v[182:185], v[102:105]
	v_mfma_f32_16x16x32_bf16 v[94:97], v[134:137], v[174:177], v[94:97]
	v_mfma_f32_16x16x32_bf16 v[86:89], v[142:145], v[174:177], v[86:89]
	v_mfma_f32_16x16x32_bf16 v[70:73], v[134:137], v[166:169], v[70:73]
	v_mfma_f32_16x16x32_bf16 v[54:57], v[142:145], v[166:169], v[54:57]
	s_setprio 0
	s_barrier
	ds_read_b128 v[162:165], v244 offset:49152
	ds_read_b128 v[166:169], v244 offset:50176
	ds_read_b128 v[170:173], v244 offset:51200
	ds_read_b128 v[174:177], v244 offset:52224
	ds_read_b128 v[178:181], v244 offset:53248
	ds_read_b128 v[182:185], v244 offset:54272
	ds_read_b128 v[186:189], v244 offset:55296
	ds_read_b128 v[190:193], v244 offset:56320
	s_mov_b32 m0, s23
	s_nop 0
	global_load_lds_dwordx4 v230, s[66:67]
	s_add_u32 m0, m0, 0x2000
	s_nop 0
	global_load_lds_dwordx4 v232, s[66:67]
	s_add_u32 s66, s70, 0x40080
	s_addc_u32 s67, s71, 0
	s_mov_b32 m0, s25
	s_nop 0
	global_load_lds_dwordx4 v230, s[66:67]
	s_add_u32 m0, m0, 0x2000
	s_nop 0
	global_load_lds_dwordx4 v232, s[66:67]
	s_nop 0
	s_mov_b32 m0, s24
	s_nop 0
	global_load_lds_dwordx4 v0, s[36:37]
	s_add_u32 m0, m0, 0x2000
	s_nop 0
	global_load_lds_dwordx4 v231, s[36:37]
	s_waitcnt vmcnt(8)
	s_waitcnt lgkmcnt(0)
	s_barrier
	s_setprio 1
	s_waitcnt lgkmcnt(7)
	v_mfma_f32_16x16x32_bf16 v[74:77], v[146:149], v[162:165], v[74:77]
	v_mfma_f32_16x16x32_bf16 v[58:61], v[154:157], v[162:165], v[58:61]
	s_waitcnt lgkmcnt(5)
	v_mfma_f32_16x16x32_bf16 v[42:45], v[146:149], v[170:173], v[42:45]
	v_mfma_f32_16x16x32_bf16 v[34:37], v[154:157], v[170:173], v[34:37]
	s_waitcnt lgkmcnt(3)
	v_mfma_f32_16x16x32_bf16 v[26:29], v[146:149], v[178:181], v[26:29]
	v_mfma_f32_16x16x32_bf16 v[18:21], v[154:157], v[178:181], v[18:21]
	s_waitcnt lgkmcnt(1)
	v_mfma_f32_16x16x32_bf16 v[10:13], v[146:149], v[186:189], v[10:13]
	v_mfma_f32_16x16x32_bf16 v[2:5], v[154:157], v[186:189], v[2:5]
	v_mfma_f32_16x16x32_bf16 v[74:77], v[150:153], v[166:169], v[74:77]
	v_mfma_f32_16x16x32_bf16 v[58:61], v[158:161], v[166:169], v[58:61]
	v_mfma_f32_16x16x32_bf16 v[42:45], v[150:153], v[174:177], v[42:45]
	v_mfma_f32_16x16x32_bf16 v[34:37], v[158:161], v[174:177], v[34:37]
	v_mfma_f32_16x16x32_bf16 v[26:29], v[150:153], v[182:185], v[26:29]
	v_mfma_f32_16x16x32_bf16 v[18:21], v[158:161], v[182:185], v[18:21]
	s_waitcnt lgkmcnt(0)
	v_mfma_f32_16x16x32_bf16 v[10:13], v[150:153], v[190:193], v[10:13]
	v_mfma_f32_16x16x32_bf16 v[2:5], v[158:161], v[190:193], v[2:5]
	s_setprio 0
	s_setprio 1
	v_mfma_f32_16x16x32_bf16 v[78:81], v[130:133], v[162:165], v[78:81]
	v_mfma_f32_16x16x32_bf16 v[66:69], v[138:141], v[162:165], v[66:69]
	v_mfma_f32_16x16x32_bf16 v[46:49], v[130:133], v[170:173], v[46:49]
	v_mfma_f32_16x16x32_bf16 v[38:41], v[138:141], v[170:173], v[38:41]
	v_mfma_f32_16x16x32_bf16 v[30:33], v[130:133], v[178:181], v[30:33]
	v_mfma_f32_16x16x32_bf16 v[22:25], v[138:141], v[178:181], v[22:25]
	v_mfma_f32_16x16x32_bf16 v[14:17], v[130:133], v[186:189], v[14:17]
	v_mfma_f32_16x16x32_bf16 v[6:9], v[138:141], v[186:189], v[6:9]
	v_mfma_f32_16x16x32_bf16 v[78:81], v[134:137], v[166:169], v[78:81]
	v_mfma_f32_16x16x32_bf16 v[66:69], v[142:145], v[166:169], v[66:69]
	v_mfma_f32_16x16x32_bf16 v[46:49], v[134:137], v[174:177], v[46:49]
	v_mfma_f32_16x16x32_bf16 v[38:41], v[142:145], v[174:177], v[38:41]
	v_mfma_f32_16x16x32_bf16 v[30:33], v[134:137], v[182:185], v[30:33]
	v_mfma_f32_16x16x32_bf16 v[22:25], v[142:145], v[182:185], v[22:25]
	v_mfma_f32_16x16x32_bf16 v[14:17], v[134:137], v[190:193], v[14:17]
	v_mfma_f32_16x16x32_bf16 v[6:9], v[142:145], v[190:193], v[6:9]
	s_setprio 0
	s_barrier
	s_add_i32 s64, s64, 2
	s_add_u32 s50, s50, 0x100
	s_addc_u32 s51, s51, 0
	s_add_u32 s52, s52, 0x100
	s_addc_u32 s53, s53, 0
	s_add_u32 s68, s68, 0x100
	s_addc_u32 s69, s69, 0
	s_cmp_gt_u32 s64, 13
	s_cbranch_scc1 .LBB0_184
	.p2align 6

; template <int MODE> ...
;     ...
;     for (int t = 0; t < nT - 1; ++t) { head(t); body(t); }
.LBB0_300:
	s_add_i32 s65, s65, 1
	s_addk_i32 s50, 0x80
	s_addk_i32 s53, 0x4000
	s_add_i32 s64, s64, 1
	s_add_u32 s46, s46, 0x48000
	s_addc_u32 s47, s47, 0
	s_add_u32 s42, s42, 0x48000
	s_addc_u32 s43, s43, 0
	s_cmp_eq_u32 s52, s65
	s_cbranch_scc1 .LBB0_281
	.p2align 6

; template <int MODE> ...
;     ...
;     for (int t = 0; t < nT - 1; ++t) { head(t); body(t); }
.LBB0_333:
	s_add_i32 s27, s27, 64
	s_addk_i32 s40, 0x100
	s_add_u32 s46, s46, 0x48000
	s_addc_u32 s47, s47, 0
	s_add_u32 s60, s60, 0x48000
	s_addc_u32 s61, s61, 0
	s_add_u32 s68, s68, 0x48000
	s_addc_u32 s69, s69, 0
	s_addk_i32 s54, 0x4000
	s_add_i32 s64, s64, 1
	s_add_u32 s70, s70, 0x48000
	s_addc_u32 s71, s71, 0
	s_add_i32 s65, s65, 1
	s_cmp_eq_u32 s65, s26
	s_cbranch_scc1 .LBB0_348
	.p2align 6

; #define PG8_STAGE(bufoff, gbase, voff) glds16s2((voff)[0], (voff)[1], (const void*)(gbase), ldsn + (unsigned)(bufoff))
; #define PG8_LDA(dst, b, h) do { _Pragma("unroll") for (int m = 0; m < 4; ++m) _Pragma("unroll") for (int k = 0; k < 2; ++k) dst[m][k] = *(const LAS bf16x8*)(lds + PG8_SA(b, h) + aoff + m * 2048 + k * 1024); } while (0)
; #define PG8_MMA(ai, bj, At, Bt) do { __builtin_amdgcn_s_setprio(1); _Pragma("unroll") for (int m = 0; m < 4; ++m) _Pragma("unroll") for (int n = 0; n < 2; ++n) _Pragma("unroll") for (int k = 0; k < 2; ++k) \
;         acc[ai][bj][m][n] = __builtin_amdgcn_mfma_f32_16x16x32_bf16(Bt[n][k], At[m][k], acc[ai][bj][m][n], 0, 0, 0); __builtin_amdgcn_s_setprio(0); } while (0)
; #define PG8_WAIT_V(n) asm volatile("s_waitcnt vmcnt(" #n ")" ::: "memory")
; #define PG8_WAIT_L(n) asm volatile("s_waitcnt lgkmcnt(" #n ")" ::: "memory")
; #define PG8_BAR __builtin_amdgcn_s_barrier()
; #define PG8_SCHED __builtin_amdgcn_sched_barrier(0)
; template <class Epi, bool ALIGN_EPI, bool EARLY_DRAIN = true, class Pre = NoPre>
; __device__ __forceinline__ void gemm_phase(LAS unsigned char* lds, const Gemm g, const StaticOrder& S, const Epi& E, int wv, const Pre& pre = Pre()) {
;     ...
;             PG8_WAIT_L(0); PG8_BAR; PG8_MMA(0, 0, At, B0); PG8_MMA(0, 1, At, B1); PG8_BAR; PG8_SCHED;
;             PG8_LDA(At, 1, 1); PG8_STAGE(PG8_SB(1, 0), b3, voffB); PG8_STAGE(PG8_SB(1, 1), b3 + bhs, voffB); PG8_STAGE(PG8_SA(1, 0), a3, voffA);
;             PG8_WAIT_V(8); PG8_WAIT_L(0); PG8_BAR; PG8_MMA(1, 0, At, B0); PG8_MMA(1, 1, At, B1); PG8_BAR; PG8_SCHED;
;         }
.LBB0_558:
	s_add_u32 s14, s86, 0x80
	s_waitcnt lgkmcnt(0)
	s_addc_u32 s15, s87, 0
	s_add_u32 s40, s84, 0x80
	s_addc_u32 s41, s85, 0
	s_barrier
	s_setprio 1
	s_waitcnt lgkmcnt(7)
	v_mfma_f32_16x16x32_bf16 v[78:81], v[178:181], v[154:157], v[78:81]
	s_waitcnt lgkmcnt(6)
	v_mfma_f32_16x16x32_bf16 v[146:149], v[182:185], v[202:205], v[78:81]
	s_waitcnt lgkmcnt(5)
	v_mfma_f32_16x16x32_bf16 v[78:81], v[178:181], v[126:129], v[92:95]
	v_mfma_f32_16x16x32_bf16 v[70:73], v[162:165], v[154:157], v[70:73]
	v_mfma_f32_16x16x32_bf16 v[74:77], v[162:165], v[126:129], v[74:77]
	s_waitcnt lgkmcnt(4)
	v_mfma_f32_16x16x32_bf16 v[150:153], v[182:185], v[158:161], v[78:81]
	s_waitcnt lgkmcnt(3)
	v_mfma_f32_16x16x32_bf16 v[78:81], v[162:165], v[194:197], v[82:85]
	v_mfma_f32_16x16x32_bf16 v[66:69], v[178:181], v[194:197], v[66:69]
	s_waitcnt lgkmcnt(1)
	v_mfma_f32_16x16x32_bf16 v[54:57], v[162:165], v[186:189], v[54:57]
	v_mfma_f32_16x16x32_bf16 v[50:53], v[178:181], v[186:189], v[50:53]
	v_mfma_f32_16x16x32_bf16 v[70:73], v[174:177], v[202:205], v[70:73]
	v_mfma_f32_16x16x32_bf16 v[74:77], v[174:177], v[158:161], v[74:77]
	v_mfma_f32_16x16x32_bf16 v[82:85], v[174:177], v[198:201], v[78:81]
	v_mfma_f32_16x16x32_bf16 v[66:69], v[182:185], v[198:201], v[66:69]
	s_waitcnt lgkmcnt(0)
	v_mfma_f32_16x16x32_bf16 v[54:57], v[174:177], v[190:193], v[54:57]
	v_mfma_f32_16x16x32_bf16 v[50:53], v[182:185], v[190:193], v[50:53]
	s_setprio 0
	s_setprio 1
	v_mfma_f32_16x16x32_bf16 v[78:81], v[138:141], v[154:157], v[86:89]
	v_mfma_f32_16x16x32_bf16 v[88:91], v[142:145], v[202:205], v[78:81]
	v_mfma_f32_16x16x32_bf16 v[78:81], v[166:169], v[154:157], v[102:105]
	v_mfma_f32_16x16x32_bf16 v[154:157], v[170:173], v[202:205], v[78:81]
	v_mfma_f32_16x16x32_bf16 v[78:81], v[138:141], v[126:129], v[96:99]
	v_mfma_f32_16x16x32_bf16 v[98:101], v[142:145], v[158:161], v[78:81]
	v_mfma_f32_16x16x32_bf16 v[78:81], v[166:169], v[126:129], v[118:121]
	v_mfma_f32_16x16x32_bf16 v[158:161], v[170:173], v[158:161], v[78:81]
	v_mfma_f32_16x16x32_bf16 v[78:81], v[138:141], v[194:197], v[122:125]
	v_mfma_f32_16x16x32_bf16 v[126:129], v[142:145], v[198:201], v[78:81]
	v_mfma_f32_16x16x32_bf16 v[78:81], v[166:169], v[194:197], v[110:113]
	v_mfma_f32_16x16x32_bf16 v[62:65], v[138:141], v[186:189], v[62:65]
	v_mfma_f32_16x16x32_bf16 v[58:61], v[166:169], v[186:189], v[58:61]
	v_mfma_f32_16x16x32_bf16 v[110:113], v[170:173], v[198:201], v[78:81]
	v_mfma_f32_16x16x32_bf16 v[62:65], v[142:145], v[190:193], v[62:65]
	v_mfma_f32_16x16x32_bf16 v[58:61], v[170:173], v[190:193], v[58:61]
	s_setprio 0
	s_barrier
	s_nop 0
	ds_read_b128 v[78:81], v245 offset:49152
	ds_read_b128 v[92:95], v245 offset:50176
	ds_read_b128 v[102:105], v245 offset:51200
	ds_read_b128 v[118:121], v245 offset:52224
	ds_read_b128 v[122:125], v245 offset:53248
	ds_read_b128 v[186:189], v245 offset:54272
	ds_read_b128 v[190:193], v245 offset:55296
	ds_read_b128 v[194:197], v245 offset:56320
	s_mov_b32 m0, s64
	s_nop 0
	global_load_lds_dwordx4 v251, s[40:41]
	s_add_u32 m0, m0, 0x2000
	s_nop 0
	global_load_lds_dwordx4 v247, s[40:41]
	s_add_u32 s40, s84, 0x580080
	s_addc_u32 s41, s85, 0
	s_mov_b32 m0, s66
	s_nop 0
	global_load_lds_dwordx4 v251, s[40:41]
	s_add_u32 m0, m0, 0x2000
	s_nop 0
	global_load_lds_dwordx4 v247, s[40:41]
	s_nop 0
	s_mov_b32 m0, s65
	s_nop 0
	global_load_lds_dwordx4 v250, s[14:15]
	s_add_u32 m0, m0, 0x2000
	s_nop 0
	global_load_lds_dwordx4 v246, s[14:15]
	s_waitcnt vmcnt(8)
	s_waitcnt lgkmcnt(0)
	s_barrier
	s_setprio 1
	s_waitcnt lgkmcnt(7)
	v_mfma_f32_16x16x32_bf16 v[38:41], v[162:165], v[78:81], v[38:41]
	v_mfma_f32_16x16x32_bf16 v[34:37], v[178:181], v[78:81], v[34:37]
	s_waitcnt lgkmcnt(5)
	v_mfma_f32_16x16x32_bf16 v[26:29], v[162:165], v[102:105], v[26:29]
	v_mfma_f32_16x16x32_bf16 v[18:21], v[178:181], v[102:105], v[18:21]
	s_waitcnt lgkmcnt(3)
	v_mfma_f32_16x16x32_bf16 v[6:9], v[162:165], v[122:125], v[6:9]
	v_mfma_f32_16x16x32_bf16 v[2:5], v[178:181], v[122:125], v[2:5]
	s_waitcnt lgkmcnt(1)
	v_mfma_f32_16x16x32_bf16 v[106:109], v[162:165], v[190:193], v[106:109]
	v_mfma_f32_16x16x32_bf16 v[130:133], v[178:181], v[190:193], v[130:133]
	v_mfma_f32_16x16x32_bf16 v[38:41], v[174:177], v[92:95], v[38:41]
	v_mfma_f32_16x16x32_bf16 v[34:37], v[182:185], v[92:95], v[34:37]
	v_mfma_f32_16x16x32_bf16 v[26:29], v[174:177], v[118:121], v[26:29]
	v_mfma_f32_16x16x32_bf16 v[18:21], v[182:185], v[118:121], v[18:21]
	v_mfma_f32_16x16x32_bf16 v[6:9], v[174:177], v[186:189], v[6:9]
	v_mfma_f32_16x16x32_bf16 v[2:5], v[182:185], v[186:189], v[2:5]
	s_waitcnt lgkmcnt(0)
	v_mfma_f32_16x16x32_bf16 v[106:109], v[174:177], v[194:197], v[106:109]
	v_mfma_f32_16x16x32_bf16 v[162:165], v[182:185], v[194:197], v[130:133]
	s_setprio 0
	s_setprio 1
	v_mfma_f32_16x16x32_bf16 v[46:49], v[138:141], v[78:81], v[46:49]
	v_mfma_f32_16x16x32_bf16 v[42:45], v[166:169], v[78:81], v[42:45]
	v_mfma_f32_16x16x32_bf16 v[78:81], v[138:141], v[190:193], v[114:117]
	v_mfma_f32_16x16x32_bf16 v[30:33], v[138:141], v[102:105], v[30:33]
	v_mfma_f32_16x16x32_bf16 v[22:25], v[166:169], v[102:105], v[22:25]
	v_mfma_f32_16x16x32_bf16 v[14:17], v[138:141], v[122:125], v[14:17]
	v_mfma_f32_16x16x32_bf16 v[10:13], v[166:169], v[122:125], v[10:13]
	v_mfma_f32_16x16x32_bf16 v[114:117], v[142:145], v[194:197], v[78:81]
	v_mfma_f32_16x16x32_bf16 v[78:81], v[166:169], v[190:193], v[134:137]
	v_mfma_f32_16x16x32_bf16 v[46:49], v[142:145], v[92:95], v[46:49]
	v_mfma_f32_16x16x32_bf16 v[42:45], v[170:173], v[92:95], v[42:45]
	v_mfma_f32_16x16x32_bf16 v[30:33], v[142:145], v[118:121], v[30:33]
	v_mfma_f32_16x16x32_bf16 v[22:25], v[170:173], v[118:121], v[22:25]
	v_mfma_f32_16x16x32_bf16 v[14:17], v[142:145], v[186:189], v[14:17]
	v_mfma_f32_16x16x32_bf16 v[10:13], v[170:173], v[186:189], v[10:13]
	v_mfma_f32_16x16x32_bf16 v[166:169], v[170:173], v[194:197], v[78:81]
	s_setprio 0
	s_barrier
	s_add_i32 s0, s0, 2
	s_add_u32 s51, s51, 0x100
	s_addc_u32 s52, s52, 0
	s_add_u32 s53, s53, 0x100
	s_addc_u32 s61, s61, 0
	s_add_u32 s42, s42, 0x100
	s_addc_u32 s43, s43, 0
	s_cmp_gt_u32 s0, 13
	s_cbranch_scc1 .LBB0_565
	.p2align 6

; #define GAS __attribute__((address_space(1)))
; template <class Epi, bool ALIGN_EPI, bool EARLY_DRAIN = true, class Pre = NoPre>
; __device__ __forceinline__ void gemm_phase(LAS unsigned char* lds, const Gemm g, const StaticOrder& S, const Epi& E, int wv, const Pre& pre = Pre()) {
;     ...
;         for (int a = 0; a < 2; ++a)
; #pragma unroll
;             for (int b = 0; b < 2; ++b)
; #pragma unroll
;                 for (int m = 0; m < 4; ++m)
; #pragma unroll
;                     for (int n = 0; n < 2; ++n) acc[a][b][m][n] = (f32x4){0.f, 0.f, 0.f, 0.f};
;     __device__ __forceinline__ void prefetch(PF& pf, const Unit& u, int wr, int wc, int fr, int fq) const {
;         const int row0 = wr * 64 + fr, col0 = u.pn * BM + wc * 32 + 8 * fq;
;         const GAS bf16_t* xp0 = (const GAS bf16_t*)xb + (size_t)(u.pm * BM + (u.pm >> 6) + row0) * D + col0;
; #pragma unroll
;         for (int m = 0; m < 4; ++m)
; #pragma unroll
;             for (int bj = 0; bj < 2; ++bj) pf.r[m][bj] = *(const GAS u32x4*)(xp0 + (size_t)(m * 16) * D + bj * HALF);
;     }
.LBB0_689:
	s_lshl_b32 s67, s0, 8
	s_ashr_i32 s0, s0, 6
	v_mbcnt_lo_u32_b32 v2, -1, 0
	v_mbcnt_hi_u32_b32 v2, -1, v2
	s_add_i32 s51, s67, s0
	s_add_i32 s0, s51, s22
	v_and_b32_e32 v3, 15, v2
	s_lshl_b32 s14, s66, 8
	v_ashrrev_i32_e32 v2, 1, v2
	v_add_u32_e32 v4, s0, v3
	s_or_b32 s50, s14, s23
	v_and_b32_e32 v2, -8, v2
	v_ashrrev_i32_e32 v5, 31, v4
	v_add_u32_e32 v2, s50, v2
	v_lshlrev_b64 v[4:5], 11, v[4:5]
	v_lshl_add_u64 v[4:5], s[78:79], 0, v[4:5]
	v_ashrrev_i32_e32 v3, 31, v2
	v_lshl_add_u64 v[2:3], v[2:3], 1, v[4:5]
	v_add_co_u32_e32 v4, vcc, s6, v2
	s_mov_b32 s0, 0x10000
	s_nop 0
	v_addc_co_u32_e32 v5, vcc, 0, v3, vcc
	global_load_dwordx4 v[118:121], v[2:3], off
	global_load_dwordx4 v[110:113], v[2:3], off offset:256
	global_load_dwordx4 v[94:97], v[4:5], off
	global_load_dwordx4 v[90:93], v[4:5], off offset:256
	v_add_co_u32_e32 v4, vcc, s0, v2
	s_mov_b32 s0, 0x18000
	s_nop 0
	v_addc_co_u32_e32 v5, vcc, 0, v3, vcc
	v_add_co_u32_e32 v2, vcc, s0, v2
	s_waitcnt lgkmcnt(10)
	global_load_dwordx4 v[78:81], v[4:5], off
	global_load_dwordx4 v[66:69], v[4:5], off offset:256
	v_addc_co_u32_e32 v3, vcc, 0, v3, vcc
	s_waitcnt lgkmcnt(8)
	global_load_dwordx4 v[54:57], v[2:3], off
	s_waitcnt lgkmcnt(2)
	global_load_dwordx4 v[42:45], v[2:3], off offset:256
	s_add_u32 s52, s60, 0x100
	s_addc_u32 s53, s61, 0
	s_add_u32 s70, s36, 0x100
	s_addc_u32 s71, s37, 0
	s_add_u32 s36, s60, 0xb0080
	v_mov_b32_e32 v2, 0
	s_addc_u32 s37, s61, 0
	s_mov_b32 s80, -2
	v_mov_b32_e32 v3, v2
	v_mov_b32_e32 v4, v2
	v_mov_b32_e32 v5, v2
	v_mov_b32_e32 v6, v2
	v_mov_b32_e32 v7, v2
	v_mov_b32_e32 v8, v2
	v_mov_b32_e32 v9, v2
	v_mov_b32_e32 v18, v2
	v_mov_b32_e32 v19, v2
	v_mov_b32_e32 v20, v2
	v_mov_b32_e32 v21, v2
	v_mov_b32_e32 v22, v2
	v_mov_b32_e32 v23, v2
	v_mov_b32_e32 v24, v2
	v_mov_b32_e32 v25, v2
	v_mov_b32_e32 v34, v2
	v_mov_b32_e32 v35, v2
	v_mov_b32_e32 v36, v2
	v_mov_b32_e32 v37, v2
	v_mov_b32_e32 v38, v2
	v_mov_b32_e32 v39, v2
	v_mov_b32_e32 v40, v2
	v_mov_b32_e32 v41, v2
	v_mov_b32_e32 v58, v2
	v_mov_b32_e32 v59, v2
	v_mov_b32_e32 v60, v2
	v_mov_b32_e32 v61, v2
	v_mov_b32_e32 v62, v2
	v_mov_b32_e32 v63, v2
	v_mov_b32_e32 v64, v2
	v_mov_b32_e32 v65, v2
	v_mov_b32_e32 v10, v2
	v_mov_b32_e32 v11, v2
	v_mov_b32_e32 v12, v2
	v_mov_b32_e32 v13, v2
	v_mov_b32_e32 v14, v2
	v_mov_b32_e32 v15, v2
	v_mov_b32_e32 v16, v2
	s_waitcnt lgkmcnt(0)
	v_mov_b32_e32 v17, v2
	v_mov_b32_e32 v26, v2
	v_mov_b32_e32 v27, v2
	v_mov_b32_e32 v28, v2
	v_mov_b32_e32 v29, v2
	v_mov_b32_e32 v30, v2
	v_mov_b32_e32 v31, v2
	v_mov_b32_e32 v32, v2
	v_mov_b32_e32 v33, v2
	v_mov_b32_e32 v46, v2
	v_mov_b32_e32 v47, v2
	v_mov_b32_e32 v48, v2
	v_mov_b32_e32 v49, v2
	v_mov_b32_e32 v50, v2
	v_mov_b32_e32 v51, v2
	v_mov_b32_e32 v52, v2
	v_mov_b32_e32 v53, v2
	v_mov_b32_e32 v70, v2
	v_mov_b32_e32 v71, v2
	v_mov_b32_e32 v72, v2
	v_mov_b32_e32 v73, v2
	v_mov_b32_e32 v74, v2
	v_mov_b32_e32 v75, v2
	v_mov_b32_e32 v76, v2
	v_mov_b32_e32 v77, v2
	v_mov_b32_e32 v82, v2
	v_mov_b32_e32 v83, v2
	v_mov_b32_e32 v84, v2
	v_mov_b32_e32 v85, v2
	v_mov_b32_e32 v86, v2
	v_mov_b32_e32 v87, v2
	v_mov_b32_e32 v88, v2
	v_mov_b32_e32 v89, v2
	v_mov_b32_e32 v106, v2
	v_mov_b32_e32 v107, v2
	v_mov_b32_e32 v108, v2
	v_mov_b32_e32 v109, v2
	v_mov_b32_e32 v114, v2
	v_mov_b32_e32 v115, v2
	v_mov_b32_e32 v116, v2
	v_mov_b32_e32 v117, v2
	v_mov_b32_e32 v130, v2
	v_mov_b32_e32 v131, v2
	v_mov_b32_e32 v132, v2
	v_mov_b32_e32 v133, v2
	v_mov_b32_e32 v134, v2
	v_mov_b32_e32 v135, v2
	v_mov_b32_e32 v136, v2
	v_mov_b32_e32 v137, v2
	v_mov_b32_e32 v150, v2
	v_mov_b32_e32 v151, v2
	v_mov_b32_e32 v152, v2
	v_mov_b32_e32 v153, v2
	v_mov_b32_e32 v154, v2
	v_mov_b32_e32 v155, v2
	v_mov_b32_e32 v156, v2
	v_mov_b32_e32 v157, v2
	v_mov_b32_e32 v98, v2
	v_mov_b32_e32 v99, v2
	v_mov_b32_e32 v100, v2
	v_mov_b32_e32 v101, v2
	v_mov_b32_e32 v102, v2
	v_mov_b32_e32 v103, v2
	v_mov_b32_e32 v104, v2
	v_mov_b32_e32 v105, v2
	v_mov_b32_e32 v122, v2
	v_mov_b32_e32 v123, v2
	v_mov_b32_e32 v124, v2
	v_mov_b32_e32 v125, v2
	v_mov_b32_e32 v126, v2
	v_mov_b32_e32 v127, v2
	v_mov_b32_e32 v128, v2
	v_mov_b32_e32 v129, v2
	v_mov_b32_e32 v138, v2
	v_mov_b32_e32 v139, v2
	v_mov_b32_e32 v140, v2
	v_mov_b32_e32 v141, v2
	v_mov_b32_e32 v142, v2
	v_mov_b32_e32 v143, v2
	v_mov_b32_e32 v144, v2
	v_mov_b32_e32 v145, v2
	v_mov_b32_e32 v162, v2
	v_mov_b32_e32 v163, v2
	v_mov_b32_e32 v164, v2
	v_mov_b32_e32 v165, v2
	v_mov_b32_e32 v170, v2
	v_mov_b32_e32 v171, v2
	v_mov_b32_e32 v172, v2
	v_mov_b32_e32 v173, v2
	.p2align 6

; #define PG8_STAGE(bufoff, gbase, voff) glds16s2((voff)[0], (voff)[1], (const void*)(gbase), ldsn + (unsigned)(bufoff))
; #define PG8_LDA(dst, b, h) do { _Pragma("unroll") for (int m = 0; m < 4; ++m) _Pragma("unroll") for (int k = 0; k < 2; ++k) dst[m][k] = *(const LAS bf16x8*)(lds + PG8_SA(b, h) + aoff + m * 2048 + k * 1024); } while (0)
; #define PG8_MMA(ai, bj, At, Bt) do { __builtin_amdgcn_s_setprio(1); _Pragma("unroll") for (int m = 0; m < 4; ++m) _Pragma("unroll") for (int n = 0; n < 2; ++n) _Pragma("unroll") for (int k = 0; k < 2; ++k) \
;         acc[ai][bj][m][n] = __builtin_amdgcn_mfma_f32_16x16x32_bf16(Bt[n][k], At[m][k], acc[ai][bj][m][n], 0, 0, 0); __builtin_amdgcn_s_setprio(0); } while (0)
; #define PG8_WAIT_V(n) asm volatile("s_waitcnt vmcnt(" #n ")" ::: "memory")
; #define PG8_WAIT_L(n) asm volatile("s_waitcnt lgkmcnt(" #n ")" ::: "memory")
; #define PG8_BAR __builtin_amdgcn_s_barrier()
; #define PG8_SCHED __builtin_amdgcn_sched_barrier(0)
; template <class Epi, bool ALIGN_EPI, bool EARLY_DRAIN = true, class Pre = NoPre>
; __device__ __forceinline__ void gemm_phase(LAS unsigned char* lds, const Gemm g, const StaticOrder& S, const Epi& E, int wv, const Pre& pre = Pre()) {
;     ...
;             PG8_WAIT_L(0); PG8_BAR; PG8_MMA(0, 0, At, B0); PG8_MMA(0, 1, At, B1); PG8_BAR; PG8_SCHED;
;             PG8_LDA(At, 1, 1); PG8_STAGE(PG8_SB(1, 0), b3, voffB); PG8_STAGE(PG8_SB(1, 1), b3 + bhs, voffB); PG8_STAGE(PG8_SA(1, 0), a3, voffA);
;             PG8_WAIT_V(8); PG8_WAIT_L(0); PG8_BAR; PG8_MMA(1, 0, At, B0); PG8_MMA(1, 1, At, B1); PG8_BAR; PG8_SCHED;
;         }
.LBB0_734:
	s_add_u32 s14, s84, 0x80
	s_waitcnt lgkmcnt(0)
	s_addc_u32 s15, s85, 0
	s_add_u32 s38, s70, 0x80
	s_addc_u32 s39, s71, 0
	s_barrier
	s_setprio 1
	s_waitcnt lgkmcnt(7)
	v_mfma_f32_16x16x32_bf16 v[98:101], v[158:161], v[130:133], v[98:101]
	s_waitcnt lgkmcnt(6)
	v_mfma_f32_16x16x32_bf16 v[162:165], v[166:169], v[202:205], v[98:101]
	v_mfma_f32_16x16x32_bf16 v[98:101], v[170:173], v[130:133], v[114:117]
	v_mfma_f32_16x16x32_bf16 v[154:157], v[174:177], v[202:205], v[98:101]
	s_waitcnt lgkmcnt(5)
	v_mfma_f32_16x16x32_bf16 v[98:101], v[158:161], v[194:197], v[118:121]
	s_waitcnt lgkmcnt(4)
	v_mfma_f32_16x16x32_bf16 v[118:121], v[166:169], v[198:201], v[98:101]
	v_mfma_f32_16x16x32_bf16 v[98:101], v[170:173], v[194:197], v[110:113]
	s_waitcnt lgkmcnt(3)
	v_mfma_f32_16x16x32_bf16 v[94:97], v[158:161], v[186:189], v[94:97]
	v_mfma_f32_16x16x32_bf16 v[90:93], v[170:173], v[186:189], v[90:93]
	s_waitcnt lgkmcnt(1)
	v_mfma_f32_16x16x32_bf16 v[78:81], v[158:161], v[178:181], v[78:81]
	v_mfma_f32_16x16x32_bf16 v[74:77], v[170:173], v[178:181], v[74:77]
	v_mfma_f32_16x16x32_bf16 v[110:113], v[174:177], v[198:201], v[98:101]
	v_mfma_f32_16x16x32_bf16 v[94:97], v[166:169], v[190:193], v[94:97]
	v_mfma_f32_16x16x32_bf16 v[90:93], v[174:177], v[190:193], v[90:93]
	s_waitcnt lgkmcnt(0)
	v_mfma_f32_16x16x32_bf16 v[78:81], v[166:169], v[182:185], v[78:81]
	v_mfma_f32_16x16x32_bf16 v[74:77], v[174:177], v[182:185], v[74:77]
	s_setprio 0
	s_setprio 1
	v_mfma_f32_16x16x32_bf16 v[98:101], v[134:137], v[130:133], v[122:125]
	v_mfma_f32_16x16x32_bf16 v[146:149], v[138:141], v[202:205], v[98:101]
	v_mfma_f32_16x16x32_bf16 v[98:101], v[142:145], v[130:133], v[126:129]
	v_mfma_f32_16x16x32_bf16 v[130:133], v[150:153], v[202:205], v[98:101]
	v_mfma_f32_16x16x32_bf16 v[98:101], v[134:137], v[194:197], v[106:109]
	v_mfma_f32_16x16x32_bf16 v[106:109], v[138:141], v[198:201], v[98:101]
	v_mfma_f32_16x16x32_bf16 v[98:101], v[142:145], v[194:197], v[102:105]
	v_mfma_f32_16x16x32_bf16 v[86:89], v[134:137], v[186:189], v[86:89]
	v_mfma_f32_16x16x32_bf16 v[82:85], v[142:145], v[186:189], v[82:85]
	v_mfma_f32_16x16x32_bf16 v[70:73], v[134:137], v[178:181], v[70:73]
	v_mfma_f32_16x16x32_bf16 v[66:69], v[142:145], v[178:181], v[66:69]
	v_mfma_f32_16x16x32_bf16 v[102:105], v[150:153], v[198:201], v[98:101]
	v_mfma_f32_16x16x32_bf16 v[86:89], v[138:141], v[190:193], v[86:89]
	v_mfma_f32_16x16x32_bf16 v[82:85], v[150:153], v[190:193], v[82:85]
	v_mfma_f32_16x16x32_bf16 v[70:73], v[138:141], v[182:185], v[70:73]
	v_mfma_f32_16x16x32_bf16 v[66:69], v[150:153], v[182:185], v[66:69]
	s_setprio 0
	s_barrier
	ds_read_b128 v[98:101], v250 offset:49152
	ds_read_b128 v[114:117], v250 offset:50176
	ds_read_b128 v[122:125], v250 offset:51200
	ds_read_b128 v[126:129], v250 offset:52224
	ds_read_b128 v[178:181], v250 offset:53248
	ds_read_b128 v[182:185], v250 offset:54272
	ds_read_b128 v[186:189], v250 offset:55296
	ds_read_b128 v[190:193], v250 offset:56320
	s_mov_b32 m0, s64
	s_nop 0
	global_load_lds_dwordx4 v230, s[38:39]
	s_add_u32 m0, m0, 0x2000
	s_nop 0
	global_load_lds_dwordx4 v232, s[38:39]
	s_add_u32 s38, s70, 0xb0080
	s_addc_u32 s39, s71, 0
	s_mov_b32 m0, s66
	s_nop 0
	global_load_lds_dwordx4 v230, s[38:39]
	s_add_u32 m0, m0, 0x2000
	s_nop 0
	global_load_lds_dwordx4 v232, s[38:39]
	s_nop 0
	s_mov_b32 m0, s65
	s_nop 0
	global_load_lds_dwordx4 v0, s[14:15]
	s_add_u32 m0, m0, 0x2000
	s_nop 0
	global_load_lds_dwordx4 v231, s[14:15]
	s_waitcnt vmcnt(8)
	s_waitcnt lgkmcnt(0)
	s_barrier
	s_setprio 1
	s_waitcnt lgkmcnt(7)
	v_mfma_f32_16x16x32_bf16 v[62:65], v[158:161], v[98:101], v[62:65]
	v_mfma_f32_16x16x32_bf16 v[58:61], v[170:173], v[98:101], v[58:61]
	s_waitcnt lgkmcnt(5)
	v_mfma_f32_16x16x32_bf16 v[46:49], v[158:161], v[122:125], v[46:49]
	v_mfma_f32_16x16x32_bf16 v[42:45], v[170:173], v[122:125], v[42:45]
	s_waitcnt lgkmcnt(3)
	v_mfma_f32_16x16x32_bf16 v[30:33], v[158:161], v[178:181], v[30:33]
	v_mfma_f32_16x16x32_bf16 v[26:29], v[170:173], v[178:181], v[26:29]
	s_waitcnt lgkmcnt(1)
	v_mfma_f32_16x16x32_bf16 v[14:17], v[158:161], v[186:189], v[14:17]
	v_mfma_f32_16x16x32_bf16 v[10:13], v[170:173], v[186:189], v[10:13]
	v_mfma_f32_16x16x32_bf16 v[62:65], v[166:169], v[114:117], v[62:65]
	v_mfma_f32_16x16x32_bf16 v[58:61], v[174:177], v[114:117], v[58:61]
	v_mfma_f32_16x16x32_bf16 v[46:49], v[166:169], v[126:129], v[46:49]
	v_mfma_f32_16x16x32_bf16 v[42:45], v[174:177], v[126:129], v[42:45]
	v_mfma_f32_16x16x32_bf16 v[30:33], v[166:169], v[182:185], v[30:33]
	v_mfma_f32_16x16x32_bf16 v[26:29], v[174:177], v[182:185], v[26:29]
	s_waitcnt lgkmcnt(0)
	v_mfma_f32_16x16x32_bf16 v[14:17], v[166:169], v[190:193], v[14:17]
	v_mfma_f32_16x16x32_bf16 v[10:13], v[174:177], v[190:193], v[10:13]
	s_setprio 0
	s_setprio 1
	v_mfma_f32_16x16x32_bf16 v[54:57], v[134:137], v[98:101], v[54:57]
	v_mfma_f32_16x16x32_bf16 v[50:53], v[142:145], v[98:101], v[50:53]
	v_mfma_f32_16x16x32_bf16 v[38:41], v[134:137], v[122:125], v[38:41]
	v_mfma_f32_16x16x32_bf16 v[34:37], v[142:145], v[122:125], v[34:37]
	v_mfma_f32_16x16x32_bf16 v[22:25], v[134:137], v[178:181], v[22:25]
	v_mfma_f32_16x16x32_bf16 v[18:21], v[142:145], v[178:181], v[18:21]
	v_mfma_f32_16x16x32_bf16 v[6:9], v[134:137], v[186:189], v[6:9]
	v_mfma_f32_16x16x32_bf16 v[2:5], v[142:145], v[186:189], v[2:5]
	v_mfma_f32_16x16x32_bf16 v[54:57], v[138:141], v[114:117], v[54:57]
	v_mfma_f32_16x16x32_bf16 v[50:53], v[150:153], v[114:117], v[50:53]
	v_mfma_f32_16x16x32_bf16 v[38:41], v[138:141], v[126:129], v[38:41]
	v_mfma_f32_16x16x32_bf16 v[34:37], v[150:153], v[126:129], v[34:37]
	v_mfma_f32_16x16x32_bf16 v[22:25], v[138:141], v[182:185], v[22:25]
	v_mfma_f32_16x16x32_bf16 v[18:21], v[150:153], v[182:185], v[18:21]
	v_mfma_f32_16x16x32_bf16 v[6:9], v[138:141], v[190:193], v[6:9]
	v_mfma_f32_16x16x32_bf16 v[2:5], v[150:153], v[190:193], v[2:5]
	s_setprio 0
	s_barrier
	s_add_i32 s0, s0, 2
	s_add_u32 s19, s19, 0x100
	s_addc_u32 s24, s24, 0
	s_add_u32 s25, s25, 0x100
	s_addc_u32 s26, s26, 0
	s_add_u32 s68, s68, 0x100
	s_addc_u32 s69, s69, 0
	s_cmp_gt_u32 s0, 41
	s_cbranch_scc1 .LBB0_741
	.p2align 6

;     __device__ __forceinline__ void operator()(f32x4 (&acc)[2][2][4][2], const Unit& u, int ui, int wr, int wc, int fr, int fq) const {
;     ...
;         if (tid == 0) {
;             __hip_atomic_fetch_add(cnt + 64 * u.pm, 1u, __ATOMIC_RELAXED, __HIP_MEMORY_SCOPE_AGENT);
;             unsigned sp = 0, ok = 1;
;             while (__hip_atomic_load(cnt + 64 * u.pm, __ATOMIC_RELAXED, __HIP_MEMORY_SCOPE_AGENT) < 4u) { __builtin_amdgcn_s_sleep(2); if (++sp > (1u << 22)) { ok = 0; break; } }
.LBB0_764:
	s_or_b64 exec, exec, s[84:85]
	s_mov_b32 s0, 0x400001
	.p2align 6
